# attention near-diagonal tiles: relative-bias LUT values fetched once and reused for the second softmax map
# speedup vs baseline: 1.0024x; 1.0024x over previous
.LBB0_677:
	s_add_i32 s2, s49, -2
	s_and_b32 s50, s2, 1
	v_lshl_add_u32 v10, s50, 14, v176
	v_lshl_add_u32 v145, v157, 4, v10
	v_lshl_add_u32 v144, v175, 4, v10
	ds_read_b128 v[2:5], v145
	ds_read_b128 v[6:9], v145 offset:256
	ds_read_b128 v[10:13], v144 offset:4096
	ds_read_b128 v[14:17], v144 offset:4352
	s_waitcnt lgkmcnt(3)
	v_mfma_f32_16x16x32_f16 v[2:5], v[2:5], v[36:39], 0
	v_cmp_gt_i32_e64 s[40:41], s24, v188
	s_waitcnt lgkmcnt(2)
	v_mfma_f32_16x16x32_f16 v[6:9], v[6:9], v[36:39], 0
	s_waitcnt lgkmcnt(0)
	v_mfma_f32_16x16x32_f16 v[22:25], v[14:17], v[40:43], v[6:9]
	v_mfma_f32_16x16x32_f16 v[18:21], v[10:13], v[40:43], v[2:5]
	s_nop 4
	v_add3_u32 v6, v189, s24, -15
	ds_read_b128 v[2:5], v145 offset:512
	ds_read_b128 v[10:13], v144 offset:4608
	v_max_i32_e32 v14, v6, v167
	ds_read_b128 v[6:9], v145 offset:768
	v_cmp_gt_i32_e32 vcc, s90, v14
	ds_read_b128 v[14:17], v144 offset:4864
	s_waitcnt lgkmcnt(3)
	v_mfma_f32_16x16x32_f16 v[2:5], v[2:5], v[36:39], 0
	s_waitcnt lgkmcnt(2)
	v_mfma_f32_16x16x32_f16 v[26:29], v[10:13], v[40:43], v[2:5]
	s_waitcnt lgkmcnt(1)
	v_mfma_f32_16x16x32_f16 v[2:5], v[6:9], v[36:39], 0
	s_waitcnt lgkmcnt(0)
	v_mfma_f32_16x16x32_f16 v[30:33], v[14:17], v[40:43], v[2:5]
	s_nop 3
	s_and_saveexec_b64 s[2:3], vcc
	s_xor_b64 s[2:3], exec, s[2:3]
	s_cbranch_execz .LBB0_679
	v_add_u32_e32 v10, s24, v165
	v_add_u32_e32 v11, 1, v10
	v_add_u32_e32 v12, 2, v10
	v_add_u32_e32 v6, 3, v10
	v_add_u32_e32 v7, 16, v10
	v_add_u32_e32 v8, 17, v10
	v_add_u32_e32 v9, 34, v10
	v_add_u32_e32 v13, 35, v10
	v_add_u32_e32 v14, 48, v10
	v_add_u32_e32 v2, 18, v10
	v_add_u32_e32 v3, 19, v10
	v_add_u32_e32 v4, 32, v10
	v_add_u32_e32 v5, 33, v10
	v_add_u32_e32 v15, 49, v10
	v_add_u32_e32 v16, 50, v10
	v_add_u32_e32 v17, 51, v10
	v_med3_i32 v211, v10, s87, v225
	v_med3_i32 v210, v11, s87, v225
	v_med3_i32 v209, v12, s87, v225
	v_med3_i32 v208, v6, s87, v225
	v_med3_i32 v207, v7, s87, v225
	v_med3_i32 v206, v8, s87, v225
	v_med3_i32 v205, v2, s87, v225
	v_med3_i32 v204, v3, s87, v225
	v_med3_i32 v203, v4, s87, v225
	v_med3_i32 v202, v5, s87, v225
	v_med3_i32 v201, v9, s87, v225
	v_med3_i32 v200, v13, s87, v225
	v_med3_i32 v199, v14, s87, v225
	v_med3_i32 v198, v15, s87, v225
	v_med3_i32 v197, v16, s87, v225
	v_med3_i32 v196, v17, s87, v225
	v_lshl_add_u32 v2, v203, 2, s91
	v_lshl_add_u32 v3, v202, 2, s91
	v_lshl_add_u32 v4, v201, 2, s91
	v_lshl_add_u32 v5, v200, 2, s91
	v_lshl_add_u32 v6, v199, 2, s91
	v_lshl_add_u32 v7, v198, 2, s91
	v_lshl_add_u32 v8, v197, 2, s91
	v_lshl_add_u32 v9, v196, 2, s91
	v_lshl_add_u32 v10, v211, 2, s91
	v_lshl_add_u32 v11, v210, 2, s91
	v_lshl_add_u32 v12, v209, 2, s91
	v_lshl_add_u32 v13, v208, 2, s91
	v_lshl_add_u32 v14, v207, 2, s91
	v_lshl_add_u32 v15, v206, 2, s91
	v_lshl_add_u32 v16, v205, 2, s91
	v_lshl_add_u32 v17, v204, 2, s91
	ds_read_b32 v228, v2 offset:512
	ds_read_b32 v229, v3 offset:512
	ds_read_b32 v230, v4 offset:512
	ds_read_b32 v231, v5 offset:512
	ds_read_b32 v232, v6 offset:512
	ds_read_b32 v233, v7 offset:512
	ds_read_b32 v234, v8 offset:512
	ds_read_b32 v235, v9 offset:512
	ds_read_b32 v236, v10 offset:512
	ds_read_b32 v237, v11 offset:512
	ds_read_b32 v238, v12 offset:512
	ds_read_b32 v239, v13 offset:512
	ds_read_b32 v240, v14 offset:512
	ds_read_b32 v241, v15 offset:512
	ds_read_b32 v242, v16 offset:512
	ds_read_b32 v243, v17 offset:512
	s_waitcnt lgkmcnt(8)
	v_fma_f32 v16, v32, s36, v234
	v_fma_f32 v17, v33, s36, v235
	v_fma_f32 v14, v30, s36, v232
	v_fma_f32 v15, v31, s36, v233
	v_fma_f32 v12, v28, s36, v230
	v_fma_f32 v13, v29, s36, v231
	v_fma_f32 v10, v26, s36, v228
	v_fma_f32 v11, v27, s36, v229
	s_waitcnt lgkmcnt(0)
	v_fma_f32 v8, v24, s36, v242
	v_fma_f32 v9, v25, s36, v243
	v_fma_f32 v6, v22, s36, v240
	v_fma_f32 v7, v23, s36, v241
	v_fma_f32 v4, v20, s36, v238
	v_fma_f32 v5, v21, s36, v239
	v_fma_f32 v2, v18, s36, v236
	v_fma_f32 v3, v19, s36, v237
.LBB0_679:
	s_or_saveexec_b64 s[2:3], s[2:3]
	v_cndmask_b32_e64 v132, v186, v187, s[40:41]
	v_mul_f32_e32 v174, 0x3fb8aa3b, v132
	s_xor_b64 exec, exec, s[2:3]
	v_fma_f32 v16, v32, s36, v174
	v_fma_f32 v17, v33, s36, v174
	v_fma_f32 v12, v28, s36, v174
	v_fma_f32 v13, v29, s36, v174
	v_fma_f32 v8, v24, s36, v174
	v_fma_f32 v9, v25, s36, v174
	v_fma_f32 v4, v20, s36, v174
	v_fma_f32 v5, v21, s36, v174
	v_fma_f32 v14, v30, s36, v174
	v_fma_f32 v15, v31, s36, v174
	v_fma_f32 v10, v26, s36, v174
	v_fma_f32 v11, v27, s36, v174
	v_fma_f32 v6, v22, s36, v174
	v_fma_f32 v7, v23, s36, v174
	v_fma_f32 v2, v18, s36, v174
	v_fma_f32 v3, v19, s36, v174
	s_or_b64 exec, exec, s[2:3]
	v_max_f32_e32 v18, v2, v3
	v_max3_f32 v18, v18, v4, v5
	v_max3_f32 v18, v18, v6, v7
	v_max3_f32 v18, v18, v8, v9
	v_max3_f32 v18, v18, v10, v11
	v_max3_f32 v18, v18, v12, v13
	v_max3_f32 v18, v18, v14, v15
	v_max3_f32 v18, v18, v16, v17
	ds_bpermute_b32 v19, v35, v18
	s_waitcnt lgkmcnt(0)
	v_max_f32_e32 v194, v18, v19
	ds_bpermute_b32 v195, v149, v194
	ds_read_b128 v[18:21], v145 offset:8192
	ds_read_b128 v[22:25], v144 offset:12288
	ds_read_b128 v[26:29], v145 offset:8448
	ds_read_b128 v[30:33], v144 offset:12544
	ds_read_b128 v[246:249], v145 offset:8704
	ds_read_b128 v[250:253], v144 offset:12800
	s_waitcnt lgkmcnt(5)
	v_mfma_f32_16x16x32_f16 v[132:135], v[18:21], v[44:47], 0
	s_waitcnt lgkmcnt(4)
	v_mfma_f32_16x16x32_f16 v[132:135], v[22:25], v[48:51], v[132:135]
	ds_read_b128 v[18:21], v145 offset:8960
	ds_read_b128 v[22:25], v144 offset:13056
	s_waitcnt lgkmcnt(5)
	v_mfma_f32_16x16x32_f16 v[136:139], v[26:29], v[44:47], 0
	s_waitcnt lgkmcnt(4)
	v_mfma_f32_16x16x32_f16 v[136:139], v[30:33], v[48:51], v[136:139]
	s_waitcnt lgkmcnt(3)
	v_mfma_f32_16x16x32_f16 v[140:143], v[246:249], v[44:47], 0
	s_waitcnt lgkmcnt(2)
	v_mfma_f32_16x16x32_f16 v[140:143], v[250:253], v[48:51], v[140:143]
	s_waitcnt lgkmcnt(1)
	v_mfma_f32_16x16x32_f16 v[144:147], v[18:21], v[44:47], 0
	s_waitcnt lgkmcnt(0)
	v_mfma_f32_16x16x32_f16 v[144:147], v[22:25], v[48:51], v[144:147]
	s_and_saveexec_b64 s[2:3], vcc
	s_xor_b64 s[2:3], exec, s[2:3]
	s_cbranch_execz .LBB0_683
	s_nop 7
	s_waitcnt lgkmcnt(8)
	v_fma_f32 v32, v146, s36, v234
	v_fma_f32 v33, v147, s36, v235
	v_fma_f32 v30, v144, s36, v232
	v_fma_f32 v31, v145, s36, v233
	v_fma_f32 v28, v142, s36, v230
	v_fma_f32 v29, v143, s36, v231
	v_fma_f32 v26, v140, s36, v228
	v_fma_f32 v27, v141, s36, v229
	s_waitcnt lgkmcnt(0)
	v_fma_f32 v24, v138, s36, v242
	v_fma_f32 v25, v139, s36, v243
	v_fma_f32 v22, v136, s36, v240
	v_fma_f32 v23, v137, s36, v241
	v_fma_f32 v20, v134, s36, v238
	v_fma_f32 v21, v135, s36, v239
	v_fma_f32 v18, v132, s36, v236
	v_fma_f32 v19, v133, s36, v237
